# FFN_IN epilogue rewritten by hand: packed f32 fma/mul/add on row pairs, one cvt_pk per pair, lo/hi 16-bit stores, SGPR-base addressing (392 -> 241 instrs per tile)
# speedup vs baseline: 1.0077x; 1.0058x over previous
.LBB0_754:
	v_mov_b32_e32 v144, 0xbfb8aa3b
	v_mov_b32_e32 v146, 1.0
	v_add_u32_e32 v204, s60, v93
	v_mul_u32_u24_e32 v185, 0x1600, v204
	v_lshl_or_b32 v204, s76, 6, v92
	v_lshl_add_u32 v185, v204, 1, v185
	v_add_u32_e32 v186, 0x1600, v185
	v_add_u32_e32 v187, 0x2c00, v185
	v_add_u32_e32 v188, 0x4200, v185
	v_add_u32_e32 v189, 0xb000, v185
	v_add_u32_e32 v190, 0xc600, v185
	v_add_u32_e32 v191, 0xdc00, v185
	v_add_u32_e32 v192, 0xf200, v185
	v_add_u32_e32 v193, 0x16000, v185
	v_add_u32_e32 v194, 0x17600, v185
	v_add_u32_e32 v195, 0x18c00, v185
	v_add_u32_e32 v196, 0x1a200, v185
	v_add_u32_e32 v197, 0x21000, v185
	v_add_u32_e32 v198, 0x22600, v185
	v_add_u32_e32 v202, 0x23c00, v185
	v_add_u32_e32 v203, 0x25200, v185
	s_waitcnt lgkmcnt(0)
	s_nop 7
	v_pk_fma_f32 v[48:49], v[48:49], v[156:157], v[172:173] op_sel_hi:[1,1,0]
	v_pk_fma_f32 v[50:51], v[50:51], v[158:159], v[172:173] op_sel_hi:[1,1,0]
	v_pk_fma_f32 v[52:53], v[52:53], v[160:161], v[172:173] op_sel_hi:[1,1,0]
	v_pk_fma_f32 v[54:55], v[54:55], v[162:163], v[172:173] op_sel_hi:[1,1,0]
	v_pk_fma_f32 v[16:17], v[16:17], v[156:157], v[176:177] op_sel_hi:[1,1,0]
	v_pk_fma_f32 v[18:19], v[18:19], v[158:159], v[176:177] op_sel_hi:[1,1,0]
	v_pk_fma_f32 v[20:21], v[20:21], v[160:161], v[176:177] op_sel_hi:[1,1,0]
	v_pk_fma_f32 v[22:23], v[22:23], v[162:163], v[176:177] op_sel_hi:[1,1,0]
	v_pk_mul_f32 v[148:149], v[48:49], v[144:145] op_sel_hi:[1,0]
	v_pk_mul_f32 v[150:151], v[50:51], v[144:145] op_sel_hi:[1,0]
	v_pk_mul_f32 v[152:153], v[52:53], v[144:145] op_sel_hi:[1,0]
	v_pk_mul_f32 v[180:181], v[54:55], v[144:145] op_sel_hi:[1,0]
	v_exp_f32_e32 v148, v148
	v_exp_f32_e32 v149, v149
	v_exp_f32_e32 v150, v150
	v_exp_f32_e32 v151, v151
	v_exp_f32_e32 v152, v152
	v_exp_f32_e32 v153, v153
	v_exp_f32_e32 v180, v180
	v_exp_f32_e32 v181, v181
	s_nop 0
	v_pk_add_f32 v[148:149], v[148:149], v[146:147] op_sel_hi:[1,0]
	v_pk_add_f32 v[150:151], v[150:151], v[146:147] op_sel_hi:[1,0]
	v_pk_add_f32 v[152:153], v[152:153], v[146:147] op_sel_hi:[1,0]
	v_pk_add_f32 v[180:181], v[180:181], v[146:147] op_sel_hi:[1,0]
	v_rcp_f32_e32 v148, v148
	v_rcp_f32_e32 v149, v149
	v_rcp_f32_e32 v150, v150
	v_rcp_f32_e32 v151, v151
	v_rcp_f32_e32 v152, v152
	v_rcp_f32_e32 v153, v153
	v_rcp_f32_e32 v180, v180
	v_rcp_f32_e32 v181, v181
	s_nop 0
	v_pk_mul_f32 v[148:149], v[48:49], v[148:149]
	v_pk_mul_f32 v[150:151], v[50:51], v[150:151]
	v_pk_mul_f32 v[152:153], v[52:53], v[152:153]
	v_pk_mul_f32 v[180:181], v[54:55], v[180:181]
	v_pk_mul_f32 v[148:149], v[16:17], v[148:149]
	v_pk_mul_f32 v[150:151], v[18:19], v[150:151]
	v_pk_mul_f32 v[152:153], v[20:21], v[152:153]
	v_pk_mul_f32 v[180:181], v[22:23], v[180:181]
	v_cvt_pk_bf16_f32 v154, v148, v149
	v_cvt_pk_bf16_f32 v182, v150, v151
	v_cvt_pk_bf16_f32 v183, v152, v153
	v_cvt_pk_bf16_f32 v184, v180, v181
	global_store_short v185, v154, s[8:9] sc1
	global_store_short_d16_hi v186, v154, s[8:9] sc1
	global_store_short v187, v182, s[8:9] sc1
	global_store_short_d16_hi v188, v182, s[8:9] sc1
	global_store_short v189, v183, s[8:9] sc1
	global_store_short_d16_hi v190, v183, s[8:9] sc1
	global_store_short v191, v184, s[8:9] sc1
	global_store_short_d16_hi v192, v184, s[8:9] sc1
	v_pk_fma_f32 v[56:57], v[56:57], v[164:165], v[172:173] op_sel_hi:[1,1,0]
	v_pk_fma_f32 v[58:59], v[58:59], v[166:167], v[172:173] op_sel_hi:[1,1,0]
	v_pk_fma_f32 v[60:61], v[60:61], v[168:169], v[172:173] op_sel_hi:[1,1,0]
	v_pk_fma_f32 v[62:63], v[62:63], v[170:171], v[172:173] op_sel_hi:[1,1,0]
	v_pk_fma_f32 v[24:25], v[24:25], v[164:165], v[176:177] op_sel_hi:[1,1,0]
	v_pk_fma_f32 v[26:27], v[26:27], v[166:167], v[176:177] op_sel_hi:[1,1,0]
	v_pk_fma_f32 v[28:29], v[28:29], v[168:169], v[176:177] op_sel_hi:[1,1,0]
	v_pk_fma_f32 v[30:31], v[30:31], v[170:171], v[176:177] op_sel_hi:[1,1,0]
	v_pk_mul_f32 v[148:149], v[56:57], v[144:145] op_sel_hi:[1,0]
	v_pk_mul_f32 v[150:151], v[58:59], v[144:145] op_sel_hi:[1,0]
	v_pk_mul_f32 v[152:153], v[60:61], v[144:145] op_sel_hi:[1,0]
	v_pk_mul_f32 v[180:181], v[62:63], v[144:145] op_sel_hi:[1,0]
	v_exp_f32_e32 v148, v148
	v_exp_f32_e32 v149, v149
	v_exp_f32_e32 v150, v150
	v_exp_f32_e32 v151, v151
	v_exp_f32_e32 v152, v152
	v_exp_f32_e32 v153, v153
	v_exp_f32_e32 v180, v180
	v_exp_f32_e32 v181, v181
	s_nop 0
	v_pk_add_f32 v[148:149], v[148:149], v[146:147] op_sel_hi:[1,0]
	v_pk_add_f32 v[150:151], v[150:151], v[146:147] op_sel_hi:[1,0]
	v_pk_add_f32 v[152:153], v[152:153], v[146:147] op_sel_hi:[1,0]
	v_pk_add_f32 v[180:181], v[180:181], v[146:147] op_sel_hi:[1,0]
	v_rcp_f32_e32 v148, v148
	v_rcp_f32_e32 v149, v149
	v_rcp_f32_e32 v150, v150
	v_rcp_f32_e32 v151, v151
	v_rcp_f32_e32 v152, v152
	v_rcp_f32_e32 v153, v153
	v_rcp_f32_e32 v180, v180
	v_rcp_f32_e32 v181, v181
	s_nop 0
	v_pk_mul_f32 v[148:149], v[56:57], v[148:149]
	v_pk_mul_f32 v[150:151], v[58:59], v[150:151]
	v_pk_mul_f32 v[152:153], v[60:61], v[152:153]
	v_pk_mul_f32 v[180:181], v[62:63], v[180:181]
	v_pk_mul_f32 v[148:149], v[24:25], v[148:149]
	v_pk_mul_f32 v[150:151], v[26:27], v[150:151]
	v_pk_mul_f32 v[152:153], v[28:29], v[152:153]
	v_pk_mul_f32 v[180:181], v[30:31], v[180:181]
	v_cvt_pk_bf16_f32 v154, v148, v149
	v_cvt_pk_bf16_f32 v182, v150, v151
	v_cvt_pk_bf16_f32 v183, v152, v153
	v_cvt_pk_bf16_f32 v184, v180, v181
	global_store_short v193, v154, s[8:9] sc1
	global_store_short_d16_hi v194, v154, s[8:9] sc1
	global_store_short v195, v182, s[8:9] sc1
	global_store_short_d16_hi v196, v182, s[8:9] sc1
	global_store_short v197, v183, s[8:9] sc1
	global_store_short_d16_hi v198, v183, s[8:9] sc1
	global_store_short v202, v184, s[8:9] sc1
	global_store_short_d16_hi v203, v184, s[8:9] sc1
	v_pk_fma_f32 v[32:33], v[32:33], v[156:157], v[174:175] op_sel_hi:[1,1,0]
	v_pk_fma_f32 v[34:35], v[34:35], v[158:159], v[174:175] op_sel_hi:[1,1,0]
	v_pk_fma_f32 v[36:37], v[36:37], v[160:161], v[174:175] op_sel_hi:[1,1,0]
	v_pk_fma_f32 v[38:39], v[38:39], v[162:163], v[174:175] op_sel_hi:[1,1,0]
	v_pk_fma_f32 v[0:1], v[0:1], v[156:157], v[178:179] op_sel_hi:[1,1,0]
	v_pk_fma_f32 v[2:3], v[2:3], v[158:159], v[178:179] op_sel_hi:[1,1,0]
	v_pk_fma_f32 v[4:5], v[4:5], v[160:161], v[178:179] op_sel_hi:[1,1,0]
	v_pk_fma_f32 v[6:7], v[6:7], v[162:163], v[178:179] op_sel_hi:[1,1,0]
	v_pk_mul_f32 v[148:149], v[32:33], v[144:145] op_sel_hi:[1,0]
	v_pk_mul_f32 v[150:151], v[34:35], v[144:145] op_sel_hi:[1,0]
	v_pk_mul_f32 v[152:153], v[36:37], v[144:145] op_sel_hi:[1,0]
	v_pk_mul_f32 v[180:181], v[38:39], v[144:145] op_sel_hi:[1,0]
	v_exp_f32_e32 v148, v148
	v_exp_f32_e32 v149, v149
	v_exp_f32_e32 v150, v150
	v_exp_f32_e32 v151, v151
	v_exp_f32_e32 v152, v152
	v_exp_f32_e32 v153, v153
	v_exp_f32_e32 v180, v180
	v_exp_f32_e32 v181, v181
	s_nop 0
	v_pk_add_f32 v[148:149], v[148:149], v[146:147] op_sel_hi:[1,0]
	v_pk_add_f32 v[150:151], v[150:151], v[146:147] op_sel_hi:[1,0]
	v_pk_add_f32 v[152:153], v[152:153], v[146:147] op_sel_hi:[1,0]
	v_pk_add_f32 v[180:181], v[180:181], v[146:147] op_sel_hi:[1,0]
	v_rcp_f32_e32 v148, v148
	v_rcp_f32_e32 v149, v149
	v_rcp_f32_e32 v150, v150
	v_rcp_f32_e32 v151, v151
	v_rcp_f32_e32 v152, v152
	v_rcp_f32_e32 v153, v153
	v_rcp_f32_e32 v180, v180
	v_rcp_f32_e32 v181, v181
	s_nop 0
	v_pk_mul_f32 v[148:149], v[32:33], v[148:149]
	v_pk_mul_f32 v[150:151], v[34:35], v[150:151]
	v_pk_mul_f32 v[152:153], v[36:37], v[152:153]
	v_pk_mul_f32 v[180:181], v[38:39], v[180:181]
	v_pk_mul_f32 v[148:149], v[0:1], v[148:149]
	v_pk_mul_f32 v[150:151], v[2:3], v[150:151]
	v_pk_mul_f32 v[152:153], v[4:5], v[152:153]
	v_pk_mul_f32 v[180:181], v[6:7], v[180:181]
	v_cvt_pk_bf16_f32 v154, v148, v149
	v_cvt_pk_bf16_f32 v182, v150, v151
	v_cvt_pk_bf16_f32 v183, v152, v153
	v_cvt_pk_bf16_f32 v184, v180, v181
	global_store_short v185, v154, s[8:9] offset:64 sc1
	global_store_short_d16_hi v186, v154, s[8:9] offset:64 sc1
	global_store_short v187, v182, s[8:9] offset:64 sc1
	global_store_short_d16_hi v188, v182, s[8:9] offset:64 sc1
	global_store_short v189, v183, s[8:9] offset:64 sc1
	global_store_short_d16_hi v190, v183, s[8:9] offset:64 sc1
	global_store_short v191, v184, s[8:9] offset:64 sc1
	global_store_short_d16_hi v192, v184, s[8:9] offset:64 sc1
	v_pk_fma_f32 v[40:41], v[40:41], v[164:165], v[174:175] op_sel_hi:[1,1,0]
	v_pk_fma_f32 v[42:43], v[42:43], v[166:167], v[174:175] op_sel_hi:[1,1,0]
	v_pk_fma_f32 v[44:45], v[44:45], v[168:169], v[174:175] op_sel_hi:[1,1,0]
	v_pk_fma_f32 v[46:47], v[46:47], v[170:171], v[174:175] op_sel_hi:[1,1,0]
	v_pk_fma_f32 v[8:9], v[8:9], v[164:165], v[178:179] op_sel_hi:[1,1,0]
	v_pk_fma_f32 v[10:11], v[10:11], v[166:167], v[178:179] op_sel_hi:[1,1,0]
	v_pk_fma_f32 v[12:13], v[12:13], v[168:169], v[178:179] op_sel_hi:[1,1,0]
	v_pk_fma_f32 v[14:15], v[14:15], v[170:171], v[178:179] op_sel_hi:[1,1,0]
	v_pk_mul_f32 v[148:149], v[40:41], v[144:145] op_sel_hi:[1,0]
	v_pk_mul_f32 v[150:151], v[42:43], v[144:145] op_sel_hi:[1,0]
	v_pk_mul_f32 v[152:153], v[44:45], v[144:145] op_sel_hi:[1,0]
	v_pk_mul_f32 v[180:181], v[46:47], v[144:145] op_sel_hi:[1,0]
	v_exp_f32_e32 v148, v148
	v_exp_f32_e32 v149, v149
	v_exp_f32_e32 v150, v150
	v_exp_f32_e32 v151, v151
	v_exp_f32_e32 v152, v152
	v_exp_f32_e32 v153, v153
	v_exp_f32_e32 v180, v180
	v_exp_f32_e32 v181, v181
	s_nop 0
	v_pk_add_f32 v[148:149], v[148:149], v[146:147] op_sel_hi:[1,0]
	v_pk_add_f32 v[150:151], v[150:151], v[146:147] op_sel_hi:[1,0]
	v_pk_add_f32 v[152:153], v[152:153], v[146:147] op_sel_hi:[1,0]
	v_pk_add_f32 v[180:181], v[180:181], v[146:147] op_sel_hi:[1,0]
	v_rcp_f32_e32 v148, v148
	v_rcp_f32_e32 v149, v149
	v_rcp_f32_e32 v150, v150
	v_rcp_f32_e32 v151, v151
	v_rcp_f32_e32 v152, v152
	v_rcp_f32_e32 v153, v153
	v_rcp_f32_e32 v180, v180
	v_rcp_f32_e32 v181, v181
	s_nop 0
	v_pk_mul_f32 v[148:149], v[40:41], v[148:149]
	v_pk_mul_f32 v[150:151], v[42:43], v[150:151]
	v_pk_mul_f32 v[152:153], v[44:45], v[152:153]
	v_pk_mul_f32 v[180:181], v[46:47], v[180:181]
	v_pk_mul_f32 v[148:149], v[8:9], v[148:149]
	v_pk_mul_f32 v[150:151], v[10:11], v[150:151]
	v_pk_mul_f32 v[152:153], v[12:13], v[152:153]
	v_pk_mul_f32 v[180:181], v[14:15], v[180:181]
	v_cvt_pk_bf16_f32 v154, v148, v149
	v_cvt_pk_bf16_f32 v182, v150, v151
	v_cvt_pk_bf16_f32 v183, v152, v153
	v_cvt_pk_bf16_f32 v184, v180, v181
	global_store_short v193, v154, s[8:9] offset:64 sc1
	global_store_short_d16_hi v194, v154, s[8:9] offset:64 sc1
	global_store_short v195, v182, s[8:9] offset:64 sc1
	global_store_short_d16_hi v196, v182, s[8:9] offset:64 sc1
	global_store_short v197, v183, s[8:9] offset:64 sc1
	global_store_short_d16_hi v198, v183, s[8:9] offset:64 sc1
	global_store_short v202, v184, s[8:9] offset:64 sc1
	global_store_short_d16_hi v203, v184, s[8:9] offset:64 sc1
	s_add_i32 s3, s3, s33
	s_cmpk_gt_i32 s3, 0x15ff
	s_cbranch_scc1 .LBB0_759

.Lgk_pfhead_p7:
	v_and_b32_e32 v152, 31, v199
	v_bfe_u32 v153, v199, 5, 1
	v_lshlrev_b32_e32 v154, 2, v153
	v_sub_u32_e32 v152, v152, v154
	v_add_u32_e32 v154, s60, v93
	v_add_lshl_u32 v152, v152, v154, 2
	v_lshlrev_b32_e32 v153, 4, v153
	global_load_dword v144, v152, s[6:7]
	v_add_u32_e32 v154, 0x10000, v152
	global_load_dword v145, v154, s[6:7]
	v_add_u32_e32 v154, 0x20000, v152
	global_load_dword v146, v154, s[6:7]
	v_add_u32_e32 v154, 0x30000, v152
	global_load_dword v147, v154, s[6:7]
	v_add_u32_e32 v154, 0x40000, v152
	global_load_dword v148, v154, s[6:7]
	v_add_u32_e32 v154, 0x50000, v152
	global_load_dword v149, v154, s[6:7]
	v_add_u32_e32 v154, 0x60000, v152
	global_load_dword v150, v154, s[6:7]
	v_add_u32_e32 v154, 0x70000, v152
	global_load_dword v151, v154, s[6:7]
	s_add_i32 s59, s60, 0xffffe000
	s_lshr_b32 s59, s59, 12
	s_mulk_i32 s59, 0x1600
	s_addk_i32 s59, 0x1600
	s_cmp_gt_i32 s4, 63
	s_cselect_b32 s59, s59, 0
	v_or_b32_e32 v154, s58, v92
	v_add_lshl_u32 v154, v154, s59, 2
	global_load_dword v172, v154, s[10:11]
	global_load_dword v174, v154, s[10:11] offset:128
	global_load_dword v176, v154, s[10:11] offset:256
	global_load_dword v178, v154, s[10:11] offset:384
	v_mov_b32_e32 v48, 0
	v_mov_b32_e32 v49, 0
	v_mov_b32_e32 v50, 0
	v_mov_b32_e32 v51, 0
	v_mov_b32_e32 v52, 0
	v_mov_b32_e32 v53, 0
	v_mov_b32_e32 v54, 0
	v_mov_b32_e32 v55, 0
	v_mov_b32_e32 v56, 0
	v_mov_b32_e32 v57, 0
	v_mov_b32_e32 v58, 0
	v_mov_b32_e32 v59, 0
	v_mov_b32_e32 v60, 0
	v_mov_b32_e32 v61, 0
	v_mov_b32_e32 v62, 0
	v_mov_b32_e32 v63, 0
	v_mov_b32_e32 v32, 0
	v_mov_b32_e32 v33, 0
	v_mov_b32_e32 v34, 0
	v_mov_b32_e32 v35, 0
	v_mov_b32_e32 v36, 0
	v_mov_b32_e32 v37, 0
	v_mov_b32_e32 v38, 0
	v_mov_b32_e32 v39, 0
	v_mov_b32_e32 v40, 0
	v_mov_b32_e32 v41, 0
	v_mov_b32_e32 v42, 0
	v_mov_b32_e32 v43, 0
	v_mov_b32_e32 v44, 0
	v_mov_b32_e32 v45, 0
	v_mov_b32_e32 v46, 0
	v_mov_b32_e32 v47, 0
	v_mov_b32_e32 v16, 0
	v_mov_b32_e32 v17, 0
	v_mov_b32_e32 v18, 0
	v_mov_b32_e32 v19, 0
	v_mov_b32_e32 v20, 0
	v_mov_b32_e32 v21, 0
	v_mov_b32_e32 v22, 0
	v_mov_b32_e32 v23, 0
	v_mov_b32_e32 v24, 0
	v_mov_b32_e32 v25, 0
	v_mov_b32_e32 v26, 0
	v_mov_b32_e32 v27, 0
	v_mov_b32_e32 v28, 0
	v_mov_b32_e32 v29, 0
	v_mov_b32_e32 v30, 0
	v_mov_b32_e32 v31, 0
	v_mov_b32_e32 v0, 0
	v_mov_b32_e32 v1, 0
	v_mov_b32_e32 v2, 0
	v_mov_b32_e32 v3, 0
	v_mov_b32_e32 v4, 0
	v_mov_b32_e32 v5, 0
	v_mov_b32_e32 v6, 0
	v_mov_b32_e32 v7, 0
	v_mov_b32_e32 v8, 0
	v_mov_b32_e32 v9, 0
	v_mov_b32_e32 v10, 0
	v_mov_b32_e32 v11, 0
	v_mov_b32_e32 v12, 0
	v_mov_b32_e32 v13, 0
	v_mov_b32_e32 v14, 0
	v_mov_b32_e32 v15, 0
	s_mov_b32 s37, 7
